# nt hint on retention scan state loads and retention-output R-state/V/K/q loads (read-once streams)
# baseline (speedup 1.0000x reference)
.LBB0_175:
	s_ashr_i32 s1, s0, 31
	s_lshr_b32 s12, s1, 24
	s_add_i32 s12, s0, s12
	s_ashr_i32 s17, s12, 8
	s_and_b32 s12, s12, 0xffffff00
	s_sub_i32 s20, s0, s12
	s_mul_hi_i32 s12, s0, 0x2aaaaaab
	s_lshr_b32 s15, s12, 31
	s_ashr_i32 s12, s12, 8
	s_add_i32 s22, s12, s15
	s_mul_hi_i32 s12, s17, 0x2aaaaaab
	s_lshr_b32 s15, s12, 31
	s_add_i32 s12, s12, s15
	s_mul_i32 s12, s12, 6
	s_sub_i32 s15, s17, s12
	v_cvt_f32_i32_e32 v0, s15
	s_mov_b32 s12, 0xc2fc0000
	s_ashr_i32 s23, s22, 31
	s_ashr_i32 s21, s20, 31
	v_sub_f32_e32 v0, 0xc0a00000, v0
	v_cmp_gt_f32_e32 vcc, s12, v0
	s_lshl_b64 s[22:23], s[22:23], 14
	s_lshl_b64 s[26:27], s[20:21], 6
	v_cndmask_b32_e32 v1, 0, v229, vcc
	v_add_f32_e32 v0, v0, v1
	s_add_u32 s22, s22, s26
	v_exp_f32_e32 v0, v0
	s_addc_u32 s21, s23, s27
	s_and_b64 s[26:27], vcc, exec
	s_cselect_b32 s23, 0xffffffc0, 0
	v_ldexp_f32 v0, v0, s23
	s_mul_i32 s23, s21, 0x1800
	s_mul_hi_u32 s26, s22, 0x1800
	s_add_i32 s26, s26, s23
	s_mul_i32 s23, s22, 0x1800
	s_add_u32 s23, s42, s23
	s_addc_u32 s27, s43, s26
	s_lshl_b32 s38, s15, 6
	s_ashr_i32 s39, s38, 31
	s_lshl_b64 s[36:37], s[38:39], 1
	s_add_u32 s26, s23, s36
	s_addc_u32 s27, s27, s37
	v_sub_f32_e32 v53, 1.0, v0
	v_lshl_add_u64 v[0:1], s[26:27], 0, v[32:33]
	v_mov_b32_e32 v85, v33
	v_lshl_add_u64 v[24:25], v[0:1], 0, v[84:85]
	s_movk_i32 s15, 0x1000
	v_add_co_u32_e32 v0, vcc, s15, v24
	s_mov_b32 s15, 0xd000
	s_nop 0
	v_addc_co_u32_e32 v1, vcc, 0, v25, vcc
	global_load_dwordx4 v[232:235], v[0:1], off offset:256 nt
	v_or_b32_e32 v52, s22, v60
	v_mov_b64_e32 v[44:45], s[42:43]
	v_mov_b32_e32 v87, v33
	v_mov_b32_e32 v89, v33
	v_mov_b32_e32 v91, v33
	v_mov_b32_e32 v93, v33
	v_mov_b32_e32 v95, v33
	s_mov_b32 s12, 0
	v_lshl_add_u64 v[96:97], s[38:39], 2, v[76:77]
	v_add_co_u32_e32 v0, vcc, s15, v24
	s_mov_b32 s15, 0x19000
	s_nop 0
	v_addc_co_u32_e32 v1, vcc, 0, v25, vcc
	global_load_dwordx4 v[0:3], v[0:1], off offset:256 nt
	v_add_co_u32_e32 v4, vcc, s15, v24
	s_mov_b32 s15, 0x25000
	s_nop 0
	v_addc_co_u32_e32 v5, vcc, 0, v25, vcc
	global_load_dwordx4 v[4:7], v[4:5], off offset:256 nt
	v_add_co_u32_e32 v8, vcc, s15, v24
	s_mov_b32 s15, 0x31000
	s_nop 0
	v_addc_co_u32_e32 v9, vcc, 0, v25, vcc
	global_load_dwordx4 v[8:11], v[8:9], off offset:256 nt
	v_add_co_u32_e32 v12, vcc, s15, v24
	s_mov_b32 s15, 0x3d000
	s_nop 0
	v_addc_co_u32_e32 v13, vcc, 0, v25, vcc
	global_load_dwordx4 v[12:15], v[12:13], off offset:256 nt
	v_add_co_u32_e32 v16, vcc, s15, v24
	s_mov_b32 s15, 0x49000
	s_nop 0
	v_addc_co_u32_e32 v17, vcc, 0, v25, vcc
	global_load_dwordx4 v[16:19], v[16:17], off offset:256 nt
	v_add_co_u32_e32 v20, vcc, s15, v24
	s_mov_b32 s15, 0x55000
	s_nop 0
	v_addc_co_u32_e32 v21, vcc, 0, v25, vcc
	global_load_dwordx4 v[20:23], v[20:21], off offset:256 nt
	v_add_co_u32_e32 v24, vcc, s15, v24
	s_lshl_b32 s15, s20, 6
	s_nop 0
	v_addc_co_u32_e32 v25, vcc, 0, v25, vcc
	global_load_dwordx4 v[24:27], v[24:25], off offset:256 nt
	s_waitcnt vmcnt(7)
	ds_write_b16 v39, v232
	ds_write_b16_d16_hi v39, v232 offset:144
	ds_write_b16 v39, v233 offset:288
	ds_write_b16_d16_hi v39, v233 offset:432
	ds_write_b16 v39, v234 offset:576
	ds_write_b16_d16_hi v39, v234 offset:720
	ds_write_b16 v39, v235 offset:864
	ds_write_b16_d16_hi v39, v235 offset:1008
	v_cmp_gt_f32_e32 vcc, s33, v53
	s_waitcnt vmcnt(6)
	ds_write_b16 v39, v0 offset:16
	ds_write_b16_d16_hi v39, v0 offset:160
	ds_write_b16 v39, v1 offset:304
	ds_write_b16_d16_hi v39, v1 offset:448
	ds_write_b16 v39, v2 offset:592
	ds_write_b16_d16_hi v39, v2 offset:736
	ds_write_b16 v39, v3 offset:880
	ds_write_b16_d16_hi v39, v3 offset:1024
	s_waitcnt vmcnt(5)
	ds_write_b16 v39, v4 offset:32
	ds_write_b16_d16_hi v39, v4 offset:176
	ds_write_b16 v39, v5 offset:320
	ds_write_b16_d16_hi v39, v5 offset:464
	ds_write_b16 v39, v6 offset:608
	ds_write_b16_d16_hi v39, v6 offset:752
	ds_write_b16 v39, v7 offset:896
	ds_write_b16_d16_hi v39, v7 offset:1040
	s_waitcnt vmcnt(4)
	ds_write_b16 v39, v8 offset:48
	ds_write_b16_d16_hi v39, v8 offset:192
	ds_write_b16 v39, v9 offset:336
	ds_write_b16_d16_hi v39, v9 offset:480
	ds_write_b16 v39, v10 offset:624
	ds_write_b16_d16_hi v39, v10 offset:768
	ds_write_b16 v39, v11 offset:912
	ds_write_b16_d16_hi v39, v11 offset:1056
	s_waitcnt vmcnt(3)
	ds_write_b16 v39, v12 offset:64
	ds_write_b16_d16_hi v39, v12 offset:208
	ds_write_b16 v39, v13 offset:352
	ds_write_b16_d16_hi v39, v13 offset:496
	ds_write_b16 v39, v14 offset:640
	ds_write_b16_d16_hi v39, v14 offset:784
	ds_write_b16 v39, v15 offset:928
	ds_write_b16_d16_hi v39, v15 offset:1072
	s_waitcnt vmcnt(2)
	ds_write_b16 v39, v16 offset:80
	ds_write_b16_d16_hi v39, v16 offset:224
	ds_write_b16 v39, v17 offset:368
	ds_write_b16_d16_hi v39, v17 offset:512
	ds_write_b16 v39, v18 offset:656
	ds_write_b16_d16_hi v39, v18 offset:800
	ds_write_b16 v39, v19 offset:944
	ds_write_b16_d16_hi v39, v19 offset:1088
	s_waitcnt vmcnt(1)
	ds_write_b16 v39, v20 offset:96
	ds_write_b16_d16_hi v39, v20 offset:240
	ds_write_b16 v39, v21 offset:384
	ds_write_b16_d16_hi v39, v21 offset:528
	ds_write_b16 v39, v22 offset:672
	ds_write_b16_d16_hi v39, v22 offset:816
	ds_write_b16 v39, v23 offset:960
	ds_write_b16_d16_hi v39, v23 offset:1104
	s_waitcnt vmcnt(0)
	ds_write_b16 v39, v24 offset:112
	ds_write_b16_d16_hi v39, v24 offset:256
	ds_write_b16 v39, v25 offset:400
	ds_write_b16_d16_hi v39, v25 offset:544
	ds_write_b16 v39, v26 offset:688
	ds_write_b16_d16_hi v39, v26 offset:832
	ds_write_b16 v39, v27 offset:976
	ds_write_b16_d16_hi v39, v27 offset:1120
	v_mad_u64_u32 v[0:1], s[26:27], v52, s5, v[44:45]
	v_or_b32_e32 v8, s15, v60
	v_mad_i32_i24 v1, s21, v207, v1
	v_ashrrev_i32_e32 v9, 31, v8
	v_lshl_add_u64 v[0:1], v[0:1], 0, s[36:37]
	v_lshlrev_b64 v[8:9], 7, v[8:9]
	v_lshl_add_u64 v[4:5], v[0:1], 0, v[86:87]
	v_lshl_add_u64 v[12:13], v[64:65], 0, v[8:9]
	v_lshl_add_u64 v[20:21], v[66:67], 0, v[8:9]
	v_mov_b64_e32 v[152:153], v[4:5]
	global_load_dwordx4 v[0:3], v[4:5], off offset:3584 nt
	s_nop 0
	global_load_dwordx4 v[4:7], v[4:5], off offset:3648 nt
	s_nop 0
	v_mov_b64_e32 v[154:155], v[12:13]
	global_load_dwordx4 v[8:11], v[12:13], off offset:16
	global_load_dwordx4 v[16:19], v[12:13], off
	s_nop 0
	v_mov_b64_e32 v[156:157], v[20:21]
	global_load_dwordx4 v[12:15], v[20:21], off offset:16
	s_nop 0
	global_load_dwordx4 v[20:23], v[20:21], off
	s_mov_b32 s98, 0x18000
	s_mov_b32 s99, 0
	v_lshl_add_u64 v[158:159], s[98:99], 0, v[152:153]
	global_load_dwordx4 v[172:175], v[158:159], off offset:3584 nt
	global_load_dwordx4 v[176:179], v[158:159], off offset:3648 nt
	global_load_dwordx4 v[180:183], v[154:155], off offset:2064
	global_load_dwordx4 v[184:187], v[154:155], off offset:2048
	global_load_dwordx4 v[188:191], v[156:157], off offset:2064
	global_load_dwordx4 v[192:195], v[156:157], off offset:2048
	s_mov_b32 s98, 0x30000
	s_mov_b32 s99, 0
	v_lshl_add_u64 v[158:159], s[98:99], 0, v[152:153]
	global_load_dwordx4 v[196:199], v[158:159], off offset:3584 nt
	global_load_dwordx4 v[200:203], v[158:159], off offset:3648 nt
	s_mov_b32 s98, 0x1000
	v_lshl_add_u64 v[158:159], s[98:99], 0, v[154:155]
	global_load_dwordx4 v[212:215], v[158:159], off offset:16
	global_load_dwordx4 v[216:219], v[158:159], off
	v_lshl_add_u64 v[158:159], s[98:99], 0, v[156:157]
	global_load_dwordx4 v[220:223], v[158:159], off offset:16
	global_load_dwordx4 v[224:227], v[158:159], off
	s_waitcnt vmcnt(14)
	v_mov_b32_e32 v27, v16
	v_lshlrev_b32_e32 v25, 16, v0
	v_lshlrev_b32_e32 v24, 16, v4
	s_waitcnt vmcnt(12)
	v_mov_b32_e32 v26, v20
	v_pk_mul_f32 v[26:27], v[26:27], v[24:25]
	s_nop 0
	v_sub_f32_e32 v26, v27, v26
	v_mul_f32_e32 v28, 0x3e000000, v26
	v_mov_b32_e32 v26, v16
	v_mov_b32_e32 v27, v20
	v_pk_mul_f32 v[24:25], v[26:27], v[24:25]
	v_mov_b32_e32 v20, v17
	v_add_f32_e32 v16, v24, v25
	v_mul_f32_e32 v29, 0x3e000000, v16
	v_and_b32_e32 v25, 0xffff0000, v0
	v_and_b32_e32 v24, 0xffff0000, v4
	v_mov_b32_e32 v16, v21
	v_pk_mul_f32 v[26:27], v[16:17], v[24:25]
	v_pk_mul_f32 v[16:17], v[20:21], v[24:25]
	v_sub_f32_e32 v0, v27, v26
	v_mul_f32_e32 v26, 0x3e000000, v0
	v_add_f32_e32 v0, v16, v17
	v_lshlrev_b32_e32 v17, 16, v1
	v_lshlrev_b32_e32 v16, 16, v5
	v_mov_b32_e32 v20, v22
	v_mov_b32_e32 v21, v18
	v_pk_mul_f32 v[20:21], v[20:21], v[16:17]
	v_mul_f32_e32 v24, 0x3e000000, v0
	v_sub_f32_e32 v0, v21, v20
	v_mov_b32_e32 v20, v18
	v_mov_b32_e32 v21, v22
	v_pk_mul_f32 v[16:17], v[20:21], v[16:17]
	v_mul_f32_e32 v25, 0x3e000000, v0
	v_add_f32_e32 v0, v16, v17
	v_mul_f32_e32 v16, 0x3e000000, v0
	v_and_b32_e32 v1, 0xffff0000, v1
	v_and_b32_e32 v0, 0xffff0000, v5
	v_mov_b32_e32 v18, v23
	v_mov_b32_e32 v22, v19
	v_pk_mul_f32 v[4:5], v[18:19], v[0:1]
	v_pk_mul_f32 v[0:1], v[22:23], v[0:1]
	v_sub_f32_e32 v4, v5, v4
	v_add_f32_e32 v0, v0, v1
	v_mul_f32_e32 v17, 0x3e000000, v4
	v_mul_f32_e32 v18, 0x3e000000, v0
	v_lshlrev_b32_e32 v1, 16, v2
	v_lshlrev_b32_e32 v0, 16, v6
	v_mov_b32_e32 v4, v12
	v_mov_b32_e32 v5, v8
	v_pk_mul_f32 v[4:5], v[4:5], v[0:1]
	s_nop 0
	v_sub_f32_e32 v4, v5, v4
	v_mul_f32_e32 v19, 0x3e000000, v4
	v_mov_b32_e32 v4, v8
	v_mov_b32_e32 v5, v12
	v_pk_mul_f32 v[0:1], v[4:5], v[0:1]
	v_mov_b32_e32 v8, v13
	v_add_f32_e32 v0, v0, v1
	v_mul_f32_e32 v20, 0x3e000000, v0
	v_and_b32_e32 v1, 0xffff0000, v2
	v_and_b32_e32 v0, 0xffff0000, v6
	v_mov_b32_e32 v12, v9
	v_pk_mul_f32 v[4:5], v[8:9], v[0:1]
	v_pk_mul_f32 v[0:1], v[12:13], v[0:1]
	v_sub_f32_e32 v2, v5, v4
	v_add_f32_e32 v0, v0, v1
	v_mul_f32_e32 v8, 0x3e000000, v0
	v_lshlrev_b32_e32 v1, 16, v3
	v_lshlrev_b32_e32 v0, 16, v7
	v_mov_b32_e32 v4, v14
	v_mov_b32_e32 v5, v10
	v_pk_mul_f32 v[4:5], v[4:5], v[0:1]
	v_mul_f32_e32 v6, 0x3e000000, v2
	v_sub_f32_e32 v2, v5, v4
	v_mov_b32_e32 v4, v10
	v_mov_b32_e32 v5, v14
	v_pk_mul_f32 v[0:1], v[4:5], v[0:1]
	v_mov_b32_e32 v10, v15
	v_add_f32_e32 v0, v0, v1
	v_mul_f32_e32 v12, 0x3e000000, v0
	v_and_b32_e32 v1, 0xffff0000, v3
	v_and_b32_e32 v0, 0xffff0000, v7
	v_mul_f32_e32 v9, 0x3e000000, v2
	v_pk_mul_f32 v[2:3], v[10:11], v[0:1]
	v_mov_b32_e32 v14, v11
	v_sub_f32_e32 v2, v3, v2
	v_mul_f32_e32 v3, 0x3e000000, v2
	v_cvt_pk_bf16_f32 v2, v19, v6
	v_cvt_pk_bf16_f32 v6, v20, v8
	v_or_b32_e32 v8, s22, v68
	v_pk_mul_f32 v[0:1], v[14:15], v[0:1]
	v_cvt_pk_bf16_f32 v3, v9, v3
	v_cvt_pk_bf16_f32 v5, v16, v18
	v_mad_u64_u32 v[8:9], s[26:27], v8, s5, v[44:45]
	v_or_b32_e32 v16, s15, v68
	v_add_f32_e32 v0, v0, v1
	v_cvt_pk_bf16_f32 v1, v25, v17
	v_mad_i32_i24 v9, s21, v207, v9
	v_ashrrev_i32_e32 v17, 31, v16
	v_mul_f32_e32 v7, 0x3e000000, v0
	v_lshl_add_u64 v[8:9], v[8:9], 0, s[36:37]
	v_lshlrev_b64 v[16:17], 7, v[16:17]
	v_cvt_pk_bf16_f32 v0, v28, v26
	v_cvt_pk_bf16_f32 v4, v29, v24
	v_cvt_pk_bf16_f32 v7, v12, v7
	v_lshl_add_u64 v[12:13], v[8:9], 0, v[86:87]
	v_lshl_add_u64 v[20:21], v[64:65], 0, v[16:17]
	v_lshl_add_u64 v[28:29], v[66:67], 0, v[16:17]
	s_waitcnt vmcnt(6)
	v_mov_b64_e32 v[8:9], v[172:173]
	v_mov_b64_e32 v[10:11], v[174:175]
	v_mov_b64_e32 v[12:13], v[176:177]
	v_mov_b64_e32 v[14:15], v[178:179]
	v_mov_b64_e32 v[16:17], v[180:181]
	v_mov_b64_e32 v[18:19], v[182:183]
	v_mov_b64_e32 v[24:25], v[184:185]
	v_mov_b64_e32 v[26:27], v[186:187]
	v_mov_b64_e32 v[20:21], v[188:189]
	v_mov_b64_e32 v[22:23], v[190:191]
	v_mov_b64_e32 v[28:29], v[192:193]
	v_mov_b64_e32 v[30:31], v[194:195]
	s_mov_b32 s98, 0x48000
	s_mov_b32 s99, 0
	v_lshl_add_u64 v[158:159], s[98:99], 0, v[152:153]
	global_load_dwordx4 v[172:175], v[158:159], off offset:3584 nt
	global_load_dwordx4 v[176:179], v[158:159], off offset:3648 nt
	s_mov_b32 s98, 0x1800
	v_lshl_add_u64 v[158:159], s[98:99], 0, v[154:155]
	global_load_dwordx4 v[180:183], v[158:159], off offset:16
	global_load_dwordx4 v[184:187], v[158:159], off
	v_lshl_add_u64 v[158:159], s[98:99], 0, v[156:157]
	global_load_dwordx4 v[188:191], v[158:159], off offset:16
	global_load_dwordx4 v[192:195], v[158:159], off
	v_lshlrev_b32_e32 v35, 16, v8
	v_lshlrev_b32_e32 v34, 16, v12
	v_mov_b32_e32 v36, v28
	v_mov_b32_e32 v37, v24
	v_pk_mul_f32 v[36:37], v[36:37], v[34:35]
	s_nop 0
	v_sub_f32_e32 v36, v37, v36
	v_mul_f32_e32 v40, 0x3e000000, v36
	v_mov_b32_e32 v36, v24
	v_mov_b32_e32 v37, v28
	v_pk_mul_f32 v[34:35], v[36:37], v[34:35]
	v_mov_b32_e32 v28, v25
	v_add_f32_e32 v24, v34, v35
	v_mul_f32_e32 v41, 0x3e000000, v24
	v_and_b32_e32 v35, 0xffff0000, v8
	v_and_b32_e32 v34, 0xffff0000, v12
	v_mov_b32_e32 v24, v29
	v_pk_mul_f32 v[36:37], v[24:25], v[34:35]
	v_pk_mul_f32 v[24:25], v[28:29], v[34:35]
	v_sub_f32_e32 v8, v37, v36
	v_mul_f32_e32 v36, 0x3e000000, v8
	v_add_f32_e32 v8, v24, v25
	v_lshlrev_b32_e32 v25, 16, v9
	v_lshlrev_b32_e32 v24, 16, v13
	v_mov_b32_e32 v28, v30
	v_mov_b32_e32 v29, v26
	v_pk_mul_f32 v[28:29], v[28:29], v[24:25]
	v_mul_f32_e32 v34, 0x3e000000, v8
	v_sub_f32_e32 v8, v29, v28
	v_mov_b32_e32 v28, v26
	v_mov_b32_e32 v29, v30
	v_pk_mul_f32 v[24:25], v[28:29], v[24:25]
	v_mul_f32_e32 v35, 0x3e000000, v8
	v_add_f32_e32 v8, v24, v25
	v_mul_f32_e32 v24, 0x3e000000, v8
	v_and_b32_e32 v9, 0xffff0000, v9
	v_and_b32_e32 v8, 0xffff0000, v13
	v_mov_b32_e32 v26, v31
	v_mov_b32_e32 v30, v27
	v_pk_mul_f32 v[12:13], v[26:27], v[8:9]
	v_pk_mul_f32 v[8:9], v[30:31], v[8:9]
	v_sub_f32_e32 v12, v13, v12
	v_add_f32_e32 v8, v8, v9
	v_mul_f32_e32 v25, 0x3e000000, v12
	v_mul_f32_e32 v26, 0x3e000000, v8
	v_lshlrev_b32_e32 v9, 16, v10
	v_lshlrev_b32_e32 v8, 16, v14
	v_mov_b32_e32 v12, v20
	v_mov_b32_e32 v13, v16
	v_pk_mul_f32 v[12:13], v[12:13], v[8:9]
	s_nop 0
	v_sub_f32_e32 v12, v13, v12
	v_mul_f32_e32 v27, 0x3e000000, v12
	v_mov_b32_e32 v12, v16
	v_mov_b32_e32 v13, v20
	v_pk_mul_f32 v[8:9], v[12:13], v[8:9]
	v_mov_b32_e32 v16, v21
	v_add_f32_e32 v8, v8, v9
	v_mul_f32_e32 v28, 0x3e000000, v8
	v_and_b32_e32 v9, 0xffff0000, v10
	v_and_b32_e32 v8, 0xffff0000, v14
	v_mov_b32_e32 v20, v17
	v_pk_mul_f32 v[12:13], v[16:17], v[8:9]
	v_pk_mul_f32 v[8:9], v[20:21], v[8:9]
	v_sub_f32_e32 v10, v13, v12
	v_add_f32_e32 v8, v8, v9
	v_mul_f32_e32 v16, 0x3e000000, v8
	v_lshlrev_b32_e32 v9, 16, v11
	v_lshlrev_b32_e32 v8, 16, v15
	v_mov_b32_e32 v12, v22
	v_mov_b32_e32 v13, v18
	v_pk_mul_f32 v[12:13], v[12:13], v[8:9]
	v_mul_f32_e32 v14, 0x3e000000, v10
	v_sub_f32_e32 v10, v13, v12
	v_mov_b32_e32 v12, v18
	v_mov_b32_e32 v13, v22
	v_pk_mul_f32 v[8:9], v[12:13], v[8:9]
	v_mov_b32_e32 v18, v23
	v_add_f32_e32 v8, v8, v9
	v_mul_f32_e32 v20, 0x3e000000, v8
	v_and_b32_e32 v9, 0xffff0000, v11
	v_and_b32_e32 v8, 0xffff0000, v15
	v_mul_f32_e32 v17, 0x3e000000, v10
	v_pk_mul_f32 v[10:11], v[18:19], v[8:9]
	v_mov_b32_e32 v22, v19
	v_sub_f32_e32 v10, v11, v10
	v_mul_f32_e32 v11, 0x3e000000, v10
	v_cvt_pk_bf16_f32 v10, v27, v14
	v_cvt_pk_bf16_f32 v14, v28, v16
	v_or_b32_e32 v16, s22, v70
	v_pk_mul_f32 v[8:9], v[22:23], v[8:9]
	v_cvt_pk_bf16_f32 v11, v17, v11
	v_cvt_pk_bf16_f32 v13, v24, v26
	v_mad_u64_u32 v[16:17], s[26:27], v16, s5, v[44:45]
	v_or_b32_e32 v24, s15, v70
	v_add_f32_e32 v8, v8, v9
	v_cvt_pk_bf16_f32 v9, v35, v25
	v_mad_i32_i24 v17, s21, v207, v17
	v_ashrrev_i32_e32 v25, 31, v24
	v_mul_f32_e32 v15, 0x3e000000, v8
	v_lshl_add_u64 v[16:17], v[16:17], 0, s[36:37]
	v_lshlrev_b64 v[24:25], 7, v[24:25]
	v_cvt_pk_bf16_f32 v8, v40, v36
	v_cvt_pk_bf16_f32 v12, v41, v34
	v_cvt_pk_bf16_f32 v15, v20, v15
	v_lshl_add_u64 v[20:21], v[16:17], 0, v[86:87]
	v_lshl_add_u64 v[28:29], v[64:65], 0, v[24:25]
	v_lshl_add_u64 v[40:41], v[66:67], 0, v[24:25]
	s_waitcnt vmcnt(6)
	v_mov_b64_e32 v[16:17], v[196:197]
	v_mov_b64_e32 v[18:19], v[198:199]
	v_mov_b64_e32 v[20:21], v[200:201]
	v_mov_b64_e32 v[22:23], v[202:203]
	v_mov_b64_e32 v[24:25], v[212:213]
	v_mov_b64_e32 v[26:27], v[214:215]
	v_mov_b64_e32 v[34:35], v[216:217]
	v_mov_b64_e32 v[36:37], v[218:219]
	v_mov_b64_e32 v[28:29], v[220:221]
	v_mov_b64_e32 v[30:31], v[222:223]
	v_mov_b64_e32 v[40:41], v[224:225]
	v_mov_b64_e32 v[42:43], v[226:227]
	v_lshlrev_b32_e32 v47, 16, v16
	v_lshlrev_b32_e32 v46, 16, v20
	v_mov_b32_e32 v48, v40
	v_mov_b32_e32 v49, v34
	v_pk_mul_f32 v[48:49], v[48:49], v[46:47]
	s_nop 0
	v_sub_f32_e32 v48, v49, v48
	v_mul_f32_e32 v50, 0x3e000000, v48
	v_mov_b32_e32 v48, v34
	v_mov_b32_e32 v49, v40
	v_pk_mul_f32 v[46:47], v[48:49], v[46:47]
	v_mov_b32_e32 v40, v35
	v_add_f32_e32 v34, v46, v47
	v_mul_f32_e32 v51, 0x3e000000, v34
	v_and_b32_e32 v47, 0xffff0000, v16
	v_and_b32_e32 v46, 0xffff0000, v20
	v_mov_b32_e32 v34, v41
	v_pk_mul_f32 v[48:49], v[34:35], v[46:47]
	v_pk_mul_f32 v[34:35], v[40:41], v[46:47]
	v_sub_f32_e32 v16, v49, v48
	v_mul_f32_e32 v48, 0x3e000000, v16
	v_add_f32_e32 v16, v34, v35
	v_lshlrev_b32_e32 v35, 16, v17
	v_lshlrev_b32_e32 v34, 16, v21
	v_mov_b32_e32 v40, v42
	v_mov_b32_e32 v41, v36
	v_pk_mul_f32 v[40:41], v[40:41], v[34:35]
	v_mul_f32_e32 v46, 0x3e000000, v16
	v_sub_f32_e32 v16, v41, v40
	v_mov_b32_e32 v40, v36
	v_mov_b32_e32 v41, v42
	v_pk_mul_f32 v[34:35], v[40:41], v[34:35]
	v_mul_f32_e32 v47, 0x3e000000, v16
	v_add_f32_e32 v16, v34, v35
	v_mul_f32_e32 v34, 0x3e000000, v16
	v_and_b32_e32 v17, 0xffff0000, v17
	v_and_b32_e32 v16, 0xffff0000, v21
	v_mov_b32_e32 v36, v43
	v_mov_b32_e32 v42, v37
	v_pk_mul_f32 v[20:21], v[36:37], v[16:17]
	v_pk_mul_f32 v[16:17], v[42:43], v[16:17]
	v_sub_f32_e32 v20, v21, v20
	v_add_f32_e32 v16, v16, v17
	v_mul_f32_e32 v35, 0x3e000000, v20
	v_mul_f32_e32 v36, 0x3e000000, v16
	v_lshlrev_b32_e32 v17, 16, v18
	v_lshlrev_b32_e32 v16, 16, v22
	v_mov_b32_e32 v20, v28
	v_mov_b32_e32 v21, v24
	v_pk_mul_f32 v[20:21], v[20:21], v[16:17]
	s_nop 0
	v_sub_f32_e32 v20, v21, v20
	v_mul_f32_e32 v37, 0x3e000000, v20
	v_mov_b32_e32 v20, v24
	v_mov_b32_e32 v21, v28
	v_pk_mul_f32 v[16:17], v[20:21], v[16:17]
	v_mov_b32_e32 v24, v29
	v_add_f32_e32 v16, v16, v17
	v_mul_f32_e32 v40, 0x3e000000, v16
	v_and_b32_e32 v17, 0xffff0000, v18
	v_and_b32_e32 v16, 0xffff0000, v22
	v_mov_b32_e32 v28, v25
	v_pk_mul_f32 v[20:21], v[24:25], v[16:17]
	v_pk_mul_f32 v[16:17], v[28:29], v[16:17]
	v_sub_f32_e32 v18, v21, v20
	v_add_f32_e32 v16, v16, v17
	v_mul_f32_e32 v24, 0x3e000000, v16
	v_lshlrev_b32_e32 v17, 16, v19
	v_lshlrev_b32_e32 v16, 16, v23
	v_mov_b32_e32 v20, v30
	v_mov_b32_e32 v21, v26
	v_pk_mul_f32 v[20:21], v[20:21], v[16:17]
	v_mul_f32_e32 v22, 0x3e000000, v18
	v_sub_f32_e32 v18, v21, v20
	v_mov_b32_e32 v20, v26
	v_mov_b32_e32 v21, v30
	v_pk_mul_f32 v[16:17], v[20:21], v[16:17]
	v_mov_b32_e32 v26, v31
	v_add_f32_e32 v16, v16, v17
	v_mul_f32_e32 v28, 0x3e000000, v16
	v_and_b32_e32 v17, 0xffff0000, v19
	v_and_b32_e32 v16, 0xffff0000, v23
	v_mul_f32_e32 v25, 0x3e000000, v18
	v_pk_mul_f32 v[18:19], v[26:27], v[16:17]
	v_mov_b32_e32 v30, v27
	v_sub_f32_e32 v18, v19, v18
	v_mul_f32_e32 v19, 0x3e000000, v18
	v_cvt_pk_bf16_f32 v18, v37, v22
	v_cvt_pk_bf16_f32 v22, v40, v24
	v_or_b32_e32 v24, s22, v72
	v_pk_mul_f32 v[16:17], v[30:31], v[16:17]
	v_cvt_pk_bf16_f32 v19, v25, v19
	v_cvt_pk_bf16_f32 v21, v34, v36
	v_mad_u64_u32 v[24:25], s[22:23], v24, s5, v[44:45]
	v_or_b32_e32 v34, s15, v72
	v_add_f32_e32 v16, v16, v17
	v_cvt_pk_bf16_f32 v17, v47, v35
	v_mad_i32_i24 v25, s21, v207, v25
	v_ashrrev_i32_e32 v35, 31, v34
	v_mul_f32_e32 v23, 0x3e000000, v16
	v_lshl_add_u64 v[24:25], v[24:25], 0, s[36:37]
	v_lshlrev_b64 v[34:35], 7, v[34:35]
	v_cvt_pk_bf16_f32 v16, v50, v48
	v_cvt_pk_bf16_f32 v23, v28, v23
	v_lshl_add_u64 v[28:29], v[24:25], 0, v[86:87]
	v_lshl_add_u64 v[40:41], v[64:65], 0, v[34:35]
	v_lshl_add_u64 v[48:49], v[66:67], 0, v[34:35]
	v_cvt_pk_bf16_f32 v20, v51, v46
	s_waitcnt vmcnt(0)
	v_mov_b64_e32 v[24:25], v[172:173]
	v_mov_b64_e32 v[26:27], v[174:175]
	v_mov_b64_e32 v[28:29], v[176:177]
	v_mov_b64_e32 v[30:31], v[178:179]
	v_mov_b64_e32 v[34:35], v[180:181]
	v_mov_b64_e32 v[36:37], v[182:183]
	v_mov_b64_e32 v[44:45], v[184:185]
	v_mov_b64_e32 v[46:47], v[186:187]
	v_mov_b64_e32 v[40:41], v[188:189]
	v_mov_b64_e32 v[42:43], v[190:191]
	v_mov_b64_e32 v[48:49], v[192:193]
	v_mov_b64_e32 v[50:51], v[194:195]
	s_lshl_b64 s[22:23], s[0:1], 14
	v_lshlrev_b32_e32 v55, 16, v24
	v_lshlrev_b32_e32 v54, 16, v28
	v_mov_b32_e32 v56, v48
	v_mov_b32_e32 v57, v44
	v_pk_mul_f32 v[56:57], v[56:57], v[54:55]
	s_nop 0
	v_sub_f32_e32 v56, v57, v56
	v_mul_f32_e32 v58, 0x3e000000, v56
	v_mov_b32_e32 v56, v44
	v_mov_b32_e32 v57, v48
	v_pk_mul_f32 v[54:55], v[56:57], v[54:55]
	v_mov_b32_e32 v48, v45
	v_add_f32_e32 v44, v54, v55
	v_mul_f32_e32 v59, 0x3e000000, v44
	v_and_b32_e32 v55, 0xffff0000, v24
	v_and_b32_e32 v54, 0xffff0000, v28
	v_mov_b32_e32 v44, v49
	v_pk_mul_f32 v[56:57], v[44:45], v[54:55]
	v_pk_mul_f32 v[44:45], v[48:49], v[54:55]
	v_sub_f32_e32 v24, v57, v56
	v_mul_f32_e32 v56, 0x3e000000, v24
	v_add_f32_e32 v24, v44, v45
	v_lshlrev_b32_e32 v45, 16, v25
	v_lshlrev_b32_e32 v44, 16, v29
	v_mov_b32_e32 v48, v50
	v_mov_b32_e32 v49, v46
	v_pk_mul_f32 v[48:49], v[48:49], v[44:45]
	v_mul_f32_e32 v54, 0x3e000000, v24
	v_sub_f32_e32 v24, v49, v48
	v_mov_b32_e32 v48, v46
	v_mov_b32_e32 v49, v50
	v_pk_mul_f32 v[44:45], v[48:49], v[44:45]
	v_mul_f32_e32 v55, 0x3e000000, v24
	v_add_f32_e32 v24, v44, v45
	v_mul_f32_e32 v44, 0x3e000000, v24
	v_and_b32_e32 v25, 0xffff0000, v25
	v_and_b32_e32 v24, 0xffff0000, v29
	v_mov_b32_e32 v46, v51
	v_mov_b32_e32 v50, v47
	v_pk_mul_f32 v[28:29], v[46:47], v[24:25]
	v_pk_mul_f32 v[24:25], v[50:51], v[24:25]
	v_sub_f32_e32 v28, v29, v28
	v_add_f32_e32 v24, v24, v25
	v_mul_f32_e32 v45, 0x3e000000, v28
	v_mul_f32_e32 v46, 0x3e000000, v24
	v_lshlrev_b32_e32 v25, 16, v26
	v_lshlrev_b32_e32 v24, 16, v30
	v_mov_b32_e32 v28, v40
	v_mov_b32_e32 v29, v34
	v_pk_mul_f32 v[28:29], v[28:29], v[24:25]
	s_nop 0
	v_sub_f32_e32 v28, v29, v28
	v_mul_f32_e32 v47, 0x3e000000, v28
	v_mov_b32_e32 v28, v34
	v_mov_b32_e32 v29, v40
	v_pk_mul_f32 v[24:25], v[28:29], v[24:25]
	v_mov_b32_e32 v34, v41
	v_add_f32_e32 v24, v24, v25
	v_mul_f32_e32 v48, 0x3e000000, v24
	v_and_b32_e32 v25, 0xffff0000, v26
	v_and_b32_e32 v24, 0xffff0000, v30
	v_mov_b32_e32 v40, v35
	v_pk_mul_f32 v[28:29], v[34:35], v[24:25]
	v_pk_mul_f32 v[24:25], v[40:41], v[24:25]
	v_sub_f32_e32 v26, v29, v28
	v_add_f32_e32 v24, v24, v25
	v_mul_f32_e32 v34, 0x3e000000, v24
	v_lshlrev_b32_e32 v25, 16, v27
	v_lshlrev_b32_e32 v24, 16, v31
	v_mov_b32_e32 v28, v42
	v_mov_b32_e32 v29, v36
	v_pk_mul_f32 v[28:29], v[28:29], v[24:25]
	v_mul_f32_e32 v30, 0x3e000000, v26
	v_sub_f32_e32 v26, v29, v28
	v_mov_b32_e32 v28, v36
	v_mov_b32_e32 v29, v42
	v_pk_mul_f32 v[24:25], v[28:29], v[24:25]
	v_mov_b32_e32 v36, v43
	v_add_f32_e32 v24, v24, v25
	v_mul_f32_e32 v40, 0x3e000000, v24
	v_and_b32_e32 v25, 0xffff0000, v27
	v_and_b32_e32 v24, 0xffff0000, v31
	v_mul_f32_e32 v35, 0x3e000000, v26
	v_pk_mul_f32 v[26:27], v[36:37], v[24:25]
	v_mov_b32_e32 v42, v37
	v_sub_f32_e32 v26, v27, v26
	v_mul_f32_e32 v27, 0x3e000000, v26
	v_pk_mul_f32 v[24:25], v[42:43], v[24:25]
	v_cvt_pk_bf16_f32 v26, v47, v30
	v_cvt_pk_bf16_f32 v27, v35, v27
	v_cvt_pk_bf16_f32 v30, v48, v34
	v_lshl_add_u64 v[34:35], v[74:75], 0, s[22:23]
	v_add_f32_e32 v24, v24, v25
	v_mul_f32_e32 v31, 0x3e000000, v24
	v_cvt_pk_bf16_f32 v25, v55, v45
	v_cvt_pk_bf16_f32 v29, v44, v46
	v_cvt_pk_bf16_f32 v31, v40, v31
	v_lshl_add_u64 v[144:145], v[34:35], 0, v[88:89]
	v_lshl_add_u64 v[146:147], v[34:35], 0, v[90:91]
	v_lshl_add_u64 v[148:149], v[34:35], 0, v[92:93]
	v_lshl_add_u64 v[150:151], v[34:35], 0, v[94:95]
	global_load_dwordx4 v[172:175], v[144:145], off nt
	global_load_dwordx4 v[176:179], v[144:145], off offset:16 nt
	global_load_dwordx4 v[180:183], v[144:145], off offset:128 nt
	global_load_dwordx4 v[184:187], v[144:145], off offset:144 nt
	global_load_dwordx4 v[188:191], v[146:147], off nt
	global_load_dwordx4 v[192:195], v[146:147], off offset:16 nt
	global_load_dwordx4 v[196:199], v[146:147], off offset:128 nt
	global_load_dwordx4 v[200:203], v[146:147], off offset:144 nt
	global_load_dwordx4 v[212:215], v[148:149], off nt
	global_load_dwordx4 v[216:219], v[148:149], off offset:16 nt
	global_load_dwordx4 v[220:223], v[148:149], off offset:128 nt
	global_load_dwordx4 v[224:227], v[148:149], off offset:144 nt
	global_load_dwordx4 v[152:155], v[150:151], off nt
	global_load_dwordx4 v[156:159], v[150:151], off offset:16 nt
	global_load_dwordx4 v[160:163], v[150:151], off offset:128 nt
	global_load_dwordx4 v[232:235], v[150:151], off offset:144 nt
	s_and_b64 s[22:23], vcc, exec
	s_cselect_b32 s1, 32, 0
	v_ldexp_f32 v34, v53, s1
	v_log_f32_e32 v34, v34
	s_waitcnt vmcnt(14)
	v_cvt_pk_bf16_f32 v172, v172, v173
	v_cvt_pk_bf16_f32 v173, v174, v175
	v_cvt_pk_bf16_f32 v174, v176, v177
	v_cvt_pk_bf16_f32 v175, v178, v179
	ds_write_b128 v63, v[172:175] offset:9216
	s_waitcnt vmcnt(12)
	v_cvt_pk_bf16_f32 v180, v180, v181
	v_cvt_pk_bf16_f32 v181, v182, v183
	v_cvt_pk_bf16_f32 v182, v184, v185
	v_cvt_pk_bf16_f32 v183, v186, v187
	ds_write_b128 v63, v[180:183] offset:9280
	s_waitcnt vmcnt(10)
	v_cvt_pk_bf16_f32 v188, v188, v189
	v_cvt_pk_bf16_f32 v189, v190, v191
	v_cvt_pk_bf16_f32 v190, v192, v193
	v_cvt_pk_bf16_f32 v191, v194, v195
	ds_write_b128 v63, v[188:191] offset:11520
	s_waitcnt vmcnt(8)
	v_cvt_pk_bf16_f32 v196, v196, v197
	v_cvt_pk_bf16_f32 v197, v198, v199
	v_cvt_pk_bf16_f32 v198, v200, v201
	v_cvt_pk_bf16_f32 v199, v202, v203
	ds_write_b128 v63, v[196:199] offset:11584
	s_waitcnt vmcnt(6)
	v_cvt_pk_bf16_f32 v212, v212, v213
	v_cvt_pk_bf16_f32 v213, v214, v215
	v_cvt_pk_bf16_f32 v214, v216, v217
	v_cvt_pk_bf16_f32 v215, v218, v219
	ds_write_b128 v63, v[212:215] offset:13824
	s_waitcnt vmcnt(4)
	v_cvt_pk_bf16_f32 v220, v220, v221
	v_cvt_pk_bf16_f32 v221, v222, v223
	v_cvt_pk_bf16_f32 v222, v224, v225
	v_cvt_pk_bf16_f32 v223, v226, v227
	ds_write_b128 v63, v[220:223] offset:13888
	s_waitcnt vmcnt(2)
	v_cvt_pk_bf16_f32 v152, v152, v153
	v_cvt_pk_bf16_f32 v153, v154, v155
	v_cvt_pk_bf16_f32 v154, v156, v157
	v_cvt_pk_bf16_f32 v155, v158, v159
	ds_write_b128 v128, v[152:155] offset:9216
	s_waitcnt vmcnt(0)
	v_cvt_pk_bf16_f32 v160, v160, v161
	v_cvt_pk_bf16_f32 v161, v162, v163
	v_cvt_pk_bf16_f32 v162, v232, v233
	v_cvt_pk_bf16_f32 v163, v234, v235
	ds_write_b128 v128, v[160:163] offset:9280
	v_cndmask_b32_e32 v35, 0, v246, vcc
	v_sub_f32_e32 v85, v34, v35
	s_waitcnt lgkmcnt(0)
	v_lshl_or_b32 v34, s0, 6, v60
	s_lshl_b32 s1, s17, 14
	v_mov_b32_e32 v53, s21
	v_subrev_u32_e32 v87, s1, v34
	v_mad_u64_u32 v[98:99], s[22:23], v52, s5, v[78:79]
	v_mad_u64_u32 v[100:101], s[22:23], v52, s5, v[80:81]
	v_lshlrev_b64 v[34:35], 11, v[52:53]
	v_mad_i32_i24 v99, s21, v207, v99
	v_mad_i32_i24 v101, s21, v207, v101
	v_lshl_add_u64 v[102:103], v[82:83], 0, v[34:35]
	v_mov_b32_e32 v91, v126
	v_cvt_pk_bf16_f32 v24, v58, v56
	v_cvt_pk_bf16_f32 v28, v59, v54
.LBB0_176:
	v_add_u32_e32 v44, s12, v87
	v_lshl_add_u64 v[34:35], v[100:101], 0, s[36:37]
	v_ashrrev_i32_e32 v45, 31, v44
	v_add_co_u32_e32 v40, vcc, 0x1d408000, v34
	v_lshlrev_b64 v[44:45], 7, v[44:45]
	s_nop 0
	v_addc_co_u32_e32 v41, vcc, 0, v35, vcc
	v_lshl_add_u64 v[48:49], v[64:65], 0, v[44:45]
	v_lshl_add_u64 v[56:57], v[66:67], 0, v[44:45]
	global_load_dwordx4 v[34:37], v[40:41], off offset:2816 nt
	s_nop 0
	global_load_dwordx4 v[40:43], v[40:41], off offset:2880 nt
	s_nop 0
	global_load_dwordx4 v[44:47], v[48:49], off offset:16
	s_nop 0
	global_load_dwordx4 v[48:51], v[48:49], off
	s_nop 0
	global_load_dwordx4 v[52:55], v[56:57], off offset:16
	s_nop 0
	global_load_dwordx4 v[56:59], v[56:57], off
	v_add_u32_e32 v93, s12, v60
	v_cmp_gt_u32_e32 vcc, v93, v61
	v_subrev_u32_e32 v141, 19, v91
	s_mov_b64 s[20:21], 0x8000
	v_lshl_add_u64 v[100:101], v[100:101], 0, s[10:11]
	s_waitcnt vmcnt(5)
	v_lshlrev_b32_e32 v131, 16, v34
	s_waitcnt vmcnt(4)
	v_lshlrev_b32_e32 v130, 16, v40
	s_waitcnt vmcnt(0)
	v_mov_b32_e32 v132, v56
	v_mov_b32_e32 v133, v48
	v_pk_mul_f32 v[132:133], v[132:133], v[130:131]
	s_nop 0
	v_sub_f32_e32 v89, v133, v132
	v_mov_b32_e32 v132, v48
	v_mov_b32_e32 v133, v56
	v_pk_mul_f32 v[130:131], v[132:133], v[130:131]
	v_mov_b32_e32 v48, v57
	v_add_f32_e32 v95, v130, v131
	v_and_b32_e32 v131, 0xffff0000, v34
	v_and_b32_e32 v130, 0xffff0000, v40
	v_mov_b32_e32 v56, v49
	v_pk_mul_f32 v[132:133], v[48:49], v[130:131]
	v_pk_mul_f32 v[48:49], v[56:57], v[130:131]
	v_mov_b32_e32 v56, v58
	v_add_f32_e32 v130, v48, v49
	v_lshlrev_b32_e32 v49, 16, v35
	v_lshlrev_b32_e32 v48, 16, v41
	v_mov_b32_e32 v57, v50
	v_pk_mul_f32 v[56:57], v[56:57], v[48:49]
	v_and_b32_e32 v35, 0xffff0000, v35
	v_sub_f32_e32 v131, v57, v56
	v_mov_b32_e32 v56, v50
	v_mov_b32_e32 v57, v58
	v_and_b32_e32 v34, 0xffff0000, v41
	v_mov_b32_e32 v50, v59
	v_mov_b32_e32 v58, v51
	v_pk_mul_f32 v[48:49], v[56:57], v[48:49]
	v_pk_mul_f32 v[40:41], v[50:51], v[34:35]
	v_pk_mul_f32 v[34:35], v[58:59], v[34:35]
	v_add_f32_e32 v48, v48, v49
	v_sub_f32_e32 v49, v41, v40
	v_add_f32_e32 v50, v34, v35
	v_lshlrev_b32_e32 v35, 16, v36
	v_lshlrev_b32_e32 v34, 16, v42
	v_mov_b32_e32 v40, v52
	v_mov_b32_e32 v41, v44
	v_pk_mul_f32 v[40:41], v[40:41], v[34:35]
	v_sub_f32_e32 v129, v133, v132
	v_sub_f32_e32 v51, v41, v40
	v_mov_b32_e32 v40, v44
	v_mov_b32_e32 v41, v52
	v_pk_mul_f32 v[34:35], v[40:41], v[34:35]
	v_mov_b32_e32 v44, v53
	v_add_f32_e32 v56, v34, v35
	v_and_b32_e32 v35, 0xffff0000, v36
	v_and_b32_e32 v34, 0xffff0000, v42
	v_mov_b32_e32 v52, v45
	v_pk_mul_f32 v[40:41], v[44:45], v[34:35]
	v_pk_mul_f32 v[34:35], v[52:53], v[34:35]
	v_sub_f32_e32 v42, v41, v40
	v_add_f32_e32 v44, v34, v35
	v_lshlrev_b32_e32 v35, 16, v37
	v_lshlrev_b32_e32 v34, 16, v43
	v_mov_b32_e32 v40, v54
	v_mov_b32_e32 v41, v46
	v_pk_mul_f32 v[40:41], v[40:41], v[34:35]
	s_nop 0
	v_sub_f32_e32 v45, v41, v40
	v_mov_b32_e32 v40, v46
	v_mov_b32_e32 v41, v54
	v_pk_mul_f32 v[34:35], v[40:41], v[34:35]
	v_mov_b32_e32 v46, v55
	v_add_f32_e32 v52, v34, v35
	v_and_b32_e32 v35, 0xffff0000, v37
	v_and_b32_e32 v34, 0xffff0000, v43
	v_mov_b32_e32 v54, v47
	v_pk_mul_f32 v[36:37], v[46:47], v[34:35]
	v_pk_mul_f32 v[34:35], v[54:55], v[34:35]
	v_sub_f32_e32 v37, v37, v36
	v_add_f32_e32 v43, v34, v35
	v_cvt_pk_bf16_f32 v35, v131, v49
	v_cvt_pk_bf16_f32 v36, v51, v42
	v_cvt_pk_bf16_f32 v41, v48, v50
	v_cvt_pk_bf16_f32 v43, v52, v43
	ds_read_b128 v[46:49], v104 offset:9216
	ds_read_b128 v[50:53], v104 offset:9280
	v_cvt_pk_bf16_f32 v42, v56, v44
	v_add_u32_e32 v44, 1, v93
	v_cvt_f32_u32_e32 v44, v44
	v_cvt_pk_bf16_f32 v34, v89, v129
	v_cvt_pk_bf16_f32 v37, v45, v37
	v_cvt_pk_bf16_f32 v40, v95, v130
	v_mul_f32_e32 v44, v85, v44
	s_waitcnt lgkmcnt(1)
	v_mfma_f32_16x16x32_bf16 v[46:49], v[46:49], v[34:37], 0
	v_exp_f32_e32 v44, v44
	v_add_u32_e32 v129, s12, v127
	v_subrev_u32_e32 v89, 51, v91
	s_waitcnt lgkmcnt(0)
	v_mfma_f32_16x16x32_bf16 v[46:49], v[50:53], v[40:43], v[46:49]
	v_cndmask_b32_e32 v89, v89, v129, vcc
	v_cvt_f32_u32_e32 v89, v89
	v_cmp_gt_u32_e32 vcc, v93, v111
	s_add_i32 s12, s12, 16
	s_cmp_lg_u32 s12, 64
	s_nop 2
	v_pk_mul_f32 v[58:59], v[44:45], v[48:49] op_sel_hi:[0,1]
	v_pk_mul_f32 v[56:57], v[44:45], v[46:47] op_sel_hi:[0,1]
	ds_read_b128 v[46:49], v106 offset:9216
	ds_read_b128 v[50:53], v106 offset:9280
	s_waitcnt lgkmcnt(1)
	v_mfma_f32_16x16x32_bf16 v[46:49], v[46:49], v[34:37], 0
	v_mul_f32_e32 v89, v85, v89
	v_exp_f32_e32 v89, v89
	s_waitcnt lgkmcnt(0)
	v_mfma_f32_16x16x32_bf16 v[46:49], v[50:53], v[40:43], v[46:49]
	s_nop 7
	v_pk_mul_f32 v[54:55], v[44:45], v[48:49] op_sel_hi:[0,1]
	v_pk_mul_f32 v[52:53], v[44:45], v[46:47] op_sel_hi:[0,1]
	ds_read_b128 v[46:49], v108 offset:9216
	ds_read_b128 v[130:133], v108 offset:9280
	s_waitcnt lgkmcnt(1)
	v_mfma_f32_16x16x32_bf16 v[46:49], v[46:49], v[34:37], 0
	s_waitcnt lgkmcnt(0)
	v_mfma_f32_16x16x32_bf16 v[46:49], v[130:133], v[40:43], v[46:49]
	ds_read_b128 v[130:133], v110 offset:9216
	ds_read_b128 v[134:137], v110 offset:9280
	s_waitcnt lgkmcnt(1)
	v_mfma_f32_16x16x32_bf16 v[130:133], v[130:133], v[34:37], 0
	s_nop 3
	v_mul_f32_e64 v50, v44, v48
	v_mul_f32_e64 v51, v44, v49
	v_pk_mul_f32 v[48:49], v[44:45], v[46:47] op_sel_hi:[0,1]
	s_waitcnt lgkmcnt(0)
	v_mfma_f32_16x16x32_bf16 v[130:133], v[134:137], v[40:43], v[130:133]
	v_subrev_u32_e32 v137, 35, v91
	s_nop 6
	v_pk_mul_f32 v[46:47], v[44:45], v[132:133] op_sel_hi:[0,1]
	v_pk_mul_f32 v[44:45], v[44:45], v[130:131] op_sel_hi:[0,1]
	v_mfma_f32_16x16x32_bf16 v[130:133], v[0:3], v[34:37], 0
	v_mfma_f32_16x16x32_bf16 v[130:133], v[4:7], v[40:43], v[130:133]
	s_nop 7
	v_mul_f32_e32 v95, v89, v130
	v_add_u32_e32 v89, -1, v129
	v_subrev_u32_e32 v130, 50, v91
	v_cndmask_b32_e32 v89, v130, v89, vcc
	v_cvt_f32_u32_e32 v89, v89
	v_cmp_gt_u32_e32 vcc, v93, v112
	v_mul_f32_e32 v89, v85, v89
	v_exp_f32_e32 v89, v89
	s_nop 0
	v_mul_f32_e32 v130, v89, v131
	v_add_u32_e32 v89, -2, v129
	v_subrev_u32_e32 v131, 49, v91
	v_cndmask_b32_e32 v89, v131, v89, vcc
	v_cvt_f32_u32_e32 v89, v89
	v_cmp_gt_u32_e32 vcc, v93, v113
	v_cvt_pk_bf16_f32 v130, v95, v130
	v_mul_f32_e32 v89, v85, v89
	v_exp_f32_e32 v89, v89
	s_nop 0
	v_mul_f32_e32 v131, v89, v132
	v_add_u32_e32 v89, -3, v129
	v_subrev_u32_e32 v132, 48, v91
	v_cndmask_b32_e32 v89, v132, v89, vcc
	v_cvt_f32_u32_e32 v89, v89
	v_cmp_gt_u32_e32 vcc, v93, v114
	v_mul_f32_e32 v89, v85, v89
	v_exp_f32_e32 v89, v89
	s_nop 0
	v_mul_f32_e32 v136, v89, v133
	v_add_u32_e32 v89, -16, v129
	v_cndmask_b32_e32 v89, v137, v89, vcc
	v_cvt_f32_u32_e32 v89, v89
	v_mfma_f32_16x16x32_bf16 v[132:135], v[8:11], v[34:37], 0
	v_cmp_gt_u32_e32 vcc, v93, v115
	v_cvt_pk_bf16_f32 v131, v131, v136
	v_mul_f32_e32 v89, v85, v89
	v_mfma_f32_16x16x32_bf16 v[132:135], v[12:15], v[40:43], v[132:135]
	v_exp_f32_e32 v89, v89
	s_nop 6
	v_mul_f32_e32 v137, v89, v132
	v_subrev_u32_e32 v89, 17, v129
	v_subrev_u32_e32 v132, 34, v91
	v_cndmask_b32_e32 v89, v132, v89, vcc
	v_cvt_f32_u32_e32 v89, v89
	v_cmp_gt_u32_e32 vcc, v93, v116
	v_subrev_u32_e32 v132, 33, v91
	v_mul_f32_e32 v89, v85, v89
	v_exp_f32_e32 v89, v89
	s_nop 0
	v_mul_f32_e32 v138, v89, v133
	v_subrev_u32_e32 v89, 18, v129
	v_cndmask_b32_e32 v89, v132, v89, vcc
	v_cvt_f32_u32_e32 v89, v89
	v_cmp_gt_u32_e32 vcc, v93, v117
	v_subrev_u32_e32 v132, 32, v91
	v_mul_f32_e32 v89, v85, v89
	v_exp_f32_e32 v89, v89
	s_nop 0
	v_mul_f32_e32 v139, v89, v134
	v_subrev_u32_e32 v89, 19, v129
	v_cndmask_b32_e32 v89, v132, v89, vcc
	v_cvt_f32_u32_e32 v89, v89
	v_cmp_gt_u32_e32 vcc, v93, v118
	v_mul_f32_e32 v89, v85, v89
	v_exp_f32_e32 v89, v89
	s_nop 0
	v_mul_f32_e32 v140, v89, v135
	v_subrev_u32_e32 v89, 32, v129
	v_cndmask_b32_e32 v89, v141, v89, vcc
	v_cvt_f32_u32_e32 v89, v89
	v_mfma_f32_16x16x32_bf16 v[132:135], v[16:19], v[34:37], 0
	v_cmp_gt_u32_e32 vcc, v93, v119
	v_mul_f32_e32 v89, v85, v89
	v_mfma_f32_16x16x32_bf16 v[132:135], v[20:23], v[40:43], v[132:135]
	v_exp_f32_e32 v89, v89
	v_mfma_f32_16x16x32_bf16 v[34:37], v[24:27], v[34:37], 0
	v_mfma_f32_16x16x32_bf16 v[34:37], v[28:31], v[40:43], v[34:37]
	s_nop 4
	v_mul_f32_e32 v141, v89, v132
	v_subrev_u32_e32 v89, 33, v129
	v_subrev_u32_e32 v132, 18, v91
	v_cndmask_b32_e32 v89, v132, v89, vcc
	v_cvt_f32_u32_e32 v89, v89
	v_cmp_gt_u32_e32 vcc, v93, v120
	v_subrev_u32_e32 v132, 17, v91
	v_subrev_u32_e32 v40, 48, v129
	v_mul_f32_e32 v89, v85, v89
	v_exp_f32_e32 v89, v89
	v_add_u32_e32 v41, -3, v91
	v_mul_f32_e32 v142, v89, v133
	v_subrev_u32_e32 v89, 34, v129
	v_cndmask_b32_e32 v89, v132, v89, vcc
	v_cvt_f32_u32_e32 v89, v89
	v_cmp_gt_u32_e32 vcc, v93, v121
	v_subrev_u32_e32 v132, 35, v129
	v_cvt_pk_bf16_f32 v133, v139, v140
	v_mul_f32_e32 v89, v85, v89
	v_exp_f32_e32 v89, v89
	s_nop 0
	v_mul_f32_e32 v143, v89, v134
	v_add_u32_e32 v89, -16, v91
	v_cndmask_b32_e32 v132, v89, v132, vcc
	v_cmp_gt_u32_e32 vcc, v93, v122
	v_cvt_f32_u32_e32 v132, v132
	v_cvt_pk_bf16_f32 v134, v141, v142
	v_mul_f32_e32 v132, v85, v132
	v_cndmask_b32_e32 v40, v41, v40, vcc
	v_cvt_f32_u32_e32 v40, v40
	v_cmp_gt_u32_e32 vcc, v93, v123
	v_add_u32_e32 v41, -2, v91
	v_exp_f32_e32 v132, v132
	v_mul_f32_e32 v40, v85, v40
	v_exp_f32_e32 v40, v40
	v_mul_f32_e32 v135, v132, v135
	v_cvt_pk_bf16_f32 v132, v137, v138
	v_mul_f32_e32 v34, v40, v34
	v_subrev_u32_e32 v40, 49, v129
	v_cndmask_b32_e32 v40, v41, v40, vcc
	v_cvt_f32_u32_e32 v40, v40
	v_cmp_gt_u32_e32 vcc, v93, v124
	v_add_u32_e32 v41, -1, v91
	v_cvt_pk_bf16_f32 v135, v143, v135
	v_mul_f32_e32 v40, v85, v40
	v_exp_f32_e32 v40, v40
	s_nop 0
	v_mul_f32_e32 v35, v40, v35
	v_subrev_u32_e32 v40, 50, v129
	v_cndmask_b32_e32 v40, v41, v40, vcc
	v_cvt_f32_u32_e32 v40, v40
	v_cmp_gt_u32_e32 vcc, v93, v125
	v_cvt_pk_bf16_f32 v136, v34, v35
	v_mul_f32_e32 v40, v85, v40
	v_exp_f32_e32 v40, v40
	s_nop 0
	v_mul_f32_e32 v36, v40, v36
	v_subrev_u32_e32 v40, 51, v129
	v_cndmask_b32_e32 v40, v91, v40, vcc
	v_cvt_f32_u32_e32 v40, v40
	v_mul_f32_e32 v40, v85, v40
	v_exp_f32_e32 v40, v40
	s_nop 0
	v_mul_f32_e32 v37, v40, v37
	v_add_u32_e32 v40, v73, v62
	v_cvt_pk_bf16_f32 v137, v36, v37
	ds_read2_b64 v[34:37], v40 offset1:4
	ds_read2_b64 v[40:43], v40 offset0:8 offset1:12
	s_waitcnt lgkmcnt(1)
	v_mfma_f32_16x16x32_bf16 v[34:37], v[34:37], v[130:133], v[56:59]
	s_nop 2
	v_add_u32_e32 v56, v105, v62
	s_waitcnt lgkmcnt(0)
	v_mfma_f32_16x16x32_bf16 v[40:43], v[40:43], v[134:137], v[34:37]
	s_nop 2
	ds_read2_b64 v[34:37], v56 offset1:4
	s_waitcnt lgkmcnt(0)
	v_mfma_f32_16x16x32_bf16 v[34:37], v[34:37], v[130:133], v[52:55]
	s_nop 2
	ds_read2_b64 v[52:55], v56 offset0:8 offset1:12
	v_add_u32_e32 v56, v107, v62
	s_waitcnt lgkmcnt(0)
	v_mfma_f32_16x16x32_bf16 v[34:37], v[52:55], v[134:137], v[34:37]
	ds_read2_b64 v[52:55], v56 offset1:4
	s_waitcnt lgkmcnt(0)
	v_mfma_f32_16x16x32_bf16 v[48:51], v[52:55], v[130:133], v[48:51]
	ds_read2_b64 v[52:55], v56 offset0:8 offset1:12
	s_waitcnt lgkmcnt(0)
	v_mfma_f32_16x16x32_bf16 v[50:53], v[52:55], v[134:137], v[48:51]
	s_nop 4
	v_add_u32_e32 v48, v109, v62
	ds_read2_b64 v[54:57], v48 offset1:4
	v_mov_b32_e32 v49, v37
	s_waitcnt lgkmcnt(0)
	v_mfma_f32_16x16x32_bf16 v[44:47], v[54:57], v[130:133], v[44:47]
	ds_read2_b64 v[54:57], v48 offset0:8 offset1:12
	v_mov_b32_e32 v48, v34
	s_waitcnt lgkmcnt(0)
	v_mfma_f32_16x16x32_bf16 v[130:133], v[54:57], v[134:137], v[44:47]
	s_nop 3
	v_mov_b32_e32 v44, v41
	v_mov_b32_e32 v45, v42
	v_mov_b32_e32 v46, v40
	v_mov_b32_e32 v47, v43
	v_pk_add_f32 v[44:45], v[44:45], v[46:47]
	v_mov_b32_e32 v46, v35
	v_mov_b32_e32 v47, v36
	v_pk_add_f32 v[46:47], v[46:47], v[48:49]
	v_add_f32_e32 v44, v44, v45
	v_pk_add_f32 v[46:47], v[46:47], v[46:47] op_sel:[0,1] op_sel_hi:[1,0]
	v_add_f32_e32 v44, 0, v44
	v_add_f32_e32 v48, v50, v51
	v_add_f32_e32 v54, v52, v53
	v_mov_b32_e32 v45, v130
	v_mov_b32_e32 v47, v131
	v_mov_b32_e32 v49, v132
	v_mov_b32_e32 v55, v133
	v_pk_add_f32 v[44:45], v[44:45], v[46:47]
	v_pk_add_f32 v[46:47], v[48:49], v[54:55]
	s_nop 0
	v_pk_add_f32 v[44:45], v[44:45], v[46:47]
	s_nop 0
	v_add_f32_e32 v44, v44, v45
	ds_bpermute_b32 v45, v69, v44
	s_waitcnt lgkmcnt(0)
	v_add_f32_e32 v44, v44, v45
	ds_bpermute_b32 v45, v71, v44
	s_waitcnt lgkmcnt(0)
	v_add_f32_e32 v45, v44, v45
	v_fmamk_f32 v59, v45, 0xbc800000, v41
	v_fmamk_f32 v55, v45, 0xbc800000, v40
	v_mul_f32_e32 v40, v59, v59
	v_fmac_f32_e32 v40, v55, v55
	v_fmamk_f32 v91, v45, 0xbc800000, v42
	v_fmac_f32_e32 v40, v91, v91
	v_fmac_f32_e32 v43, 0xbc800000, v45
	v_fmac_f32_e32 v40, v43, v43
	v_fmamk_f32 v58, v45, 0xbc800000, v34
	v_fmac_f32_e32 v40, v58, v58
	v_fmamk_f32 v57, v45, 0xbc800000, v35
	v_mul_f32_e32 v44, 0x3c800000, v45
	v_fmac_f32_e32 v40, v57, v57
	v_fmamk_f32 v36, v45, 0xbc800000, v36
	v_fmac_f32_e32 v40, v36, v36
	v_fmac_f32_e32 v37, 0xbc800000, v45
	v_pk_add_f32 v[50:51], v[50:51], v[44:45] op_sel_hi:[1,0] neg_lo:[0,1] neg_hi:[0,1]
	v_fmac_f32_e32 v40, v37, v37
	v_pk_mul_f32 v[34:35], v[50:51], v[50:51]
	v_pk_add_f32 v[48:49], v[52:53], v[44:45] op_sel_hi:[1,0] neg_lo:[0,1] neg_hi:[0,1]
	v_add_f32_e32 v34, v34, v40
	v_add_f32_e32 v40, v35, v34
	v_pk_mul_f32 v[34:35], v[48:49], v[48:49]
	v_pk_add_f32 v[46:47], v[130:131], v[44:45] op_sel_hi:[1,0] neg_lo:[0,1] neg_hi:[0,1]
	v_add_f32_e32 v34, v34, v40
	v_add_f32_e32 v40, v35, v34
	v_pk_mul_f32 v[34:35], v[46:47], v[46:47]
	v_pk_add_f32 v[44:45], v[132:133], v[44:45] op_sel_hi:[1,0] neg_lo:[0,1] neg_hi:[0,1]
	v_add_f32_e32 v34, v34, v40
	v_add_f32_e32 v40, v35, v34
	v_pk_mul_f32 v[34:35], v[44:45], v[44:45]
	v_lshl_add_u64 v[52:53], v[98:99], 0, s[36:37]
	global_load_dwordx2 v[144:145], v[52:53], off offset:-64
	global_load_dwordx4 v[152:155], v[96:97], off
	global_load_dwordx2 v[146:147], v[52:53], off offset:-32
	global_load_dwordx4 v[156:159], v[96:97], off offset:64
	global_load_dwordx2 v[148:149], v[52:53], off
	global_load_dwordx4 v[160:163], v[96:97], off offset:128
	global_load_dwordx2 v[150:151], v[52:53], off offset:32
	global_load_dwordx4 v[172:175], v[96:97], off offset:192
	v_add_f32_e32 v34, v34, v40
	v_add_f32_e32 v34, v35, v34
	ds_bpermute_b32 v35, v69, v34
	v_lshl_add_u64 v[98:99], v[98:99], 0, s[10:11]
	s_waitcnt lgkmcnt(0)
	v_add_f32_e32 v34, v34, v35
	ds_bpermute_b32 v35, v71, v34
	s_waitcnt lgkmcnt(0)
	v_add_f32_e32 v34, v34, v35
	v_fmamk_f32 v34, v34, 0x3c800000, v206
	v_cmp_gt_f32_e32 vcc, s33, v34
	v_mul_f32_e32 v35, 0x4b800000, v34
	s_nop 0
	v_cndmask_b32_e32 v34, v34, v35, vcc
	v_rsq_f32_e32 v34, v34
	s_nop 0
	v_mul_f32_e32 v35, 0x45800000, v34
	v_cndmask_b32_e32 v56, v34, v35, vcc
	v_mul_f32_e32 v41, v55, v56
	v_mul_f32_e32 v55, v91, v56
	v_mul_f32_e32 v43, v43, v56
	v_mov_b32_e32 v91, v89
	s_waitcnt vmcnt(0)
	v_mov_b32_e32 v34, v144
	v_mov_b32_e32 v35, v145
	v_lshlrev_b32_e32 v40, 16, v34
	v_lshlrev_b32_e32 v54, 16, v35
	v_and_b32_e32 v42, 0xffff0000, v35
	v_mul_f32_e32 v35, 0xbfb8aa3b, v40
	v_exp_f32_e32 v35, v35
	v_and_b32_e32 v34, 0xffff0000, v34
	v_mov_b32_e32 v130, v152
	v_mov_b32_e32 v131, v153
	v_mov_b32_e32 v132, v154
	v_mov_b32_e32 v133, v155
	v_mov_b32_e32 v135, v130
	v_add_f32_e32 v35, 1.0, v35
	v_rcp_f32_e32 v134, v35
	v_mul_f32_e32 v35, 0xbfb8aa3b, v34
	v_exp_f32_e32 v35, v35
	v_pk_mul_f32 v[40:41], v[134:135], v[40:41]
	s_nop 0
	v_mul_f32_e32 v40, v40, v41
	v_add_f32_e32 v35, 1.0, v35
	v_rcp_f32_e32 v130, v35
	v_mul_f32_e32 v35, v59, v56
	v_mul_f32_e32 v135, v36, v56
	v_pk_mul_f32 v[34:35], v[130:131], v[34:35]
	s_nop 0
	v_mul_f32_e32 v41, v34, v35
	v_mul_f32_e32 v34, 0xbfb8aa3b, v54
	v_exp_f32_e32 v34, v34
	v_mov_b32_e32 v35, v132
	v_mul_f32_e32 v131, v58, v56
	v_add_f32_e32 v34, 1.0, v34
	v_rcp_f32_e32 v34, v34
	s_nop 0
	v_pk_mul_f32 v[34:35], v[34:35], v[54:55]
	s_nop 0
	v_mul_f32_e32 v54, v34, v35
	v_mul_f32_e32 v34, 0xbfb8aa3b, v42
	v_exp_f32_e32 v34, v34
	s_nop 0
	v_add_f32_e32 v34, 1.0, v34
	v_rcp_f32_e32 v132, v34
	s_nop 0
	v_pk_mul_f32 v[34:35], v[132:133], v[42:43]
	s_nop 0
	v_mul_f32_e32 v35, v34, v35
	v_cvt_pk_bf16_f32 v35, v54, v35
	v_lshl_add_u64 v[54:55], v[102:103], 0, s[36:37]
	v_cvt_pk_bf16_f32 v34, v40, v41
	global_store_dwordx2 v[54:55], v[34:35], off offset:-64
	s_nop 0
	v_mul_f32_e32 v133, v57, v56
	v_lshl_add_u64 v[102:103], v[102:103], 0, s[20:21]
	v_mov_b32_e32 v34, v146
	v_mov_b32_e32 v35, v147
	v_lshlrev_b32_e32 v130, 16, v34
	v_and_b32_e32 v132, 0xffff0000, v34
	v_lshlrev_b32_e32 v134, 16, v35
	v_and_b32_e32 v34, 0xffff0000, v35
	v_mul_f32_e32 v35, 0xbfb8aa3b, v130
	v_exp_f32_e32 v35, v35
	v_mov_b32_e32 v40, v156
	v_mov_b32_e32 v41, v157
	v_mov_b32_e32 v42, v158
	v_mov_b32_e32 v43, v159
	v_mov_b32_e32 v137, v40
	v_add_f32_e32 v35, 1.0, v35
	v_rcp_f32_e32 v136, v35
	v_mul_f32_e32 v35, 0xbfb8aa3b, v132
	v_exp_f32_e32 v35, v35
	v_pk_mul_f32 v[58:59], v[136:137], v[130:131]
	s_nop 0
	v_mul_f32_e32 v58, v58, v59
	v_add_f32_e32 v35, 1.0, v35
	v_rcp_f32_e32 v40, v35
	v_mul_f32_e32 v35, 0xbfb8aa3b, v134
	v_exp_f32_e32 v35, v35
	v_mul_f32_e32 v59, v51, v56
	v_pk_mul_f32 v[40:41], v[40:41], v[132:133]
	v_mul_f32_e32 v131, v48, v56
	v_add_f32_e32 v35, 1.0, v35
	v_mul_f32_e32 v57, v40, v41
	v_rcp_f32_e32 v40, v35
	v_mul_f32_e32 v35, 0xbfb8aa3b, v34
	v_exp_f32_e32 v35, v35
	v_mov_b32_e32 v41, v42
	v_pk_mul_f32 v[40:41], v[40:41], v[134:135]
	v_mul_f32_e32 v51, v45, v56
	v_add_f32_e32 v35, 1.0, v35
	v_rcp_f32_e32 v42, v35
	v_mul_f32_e32 v35, v37, v56
	v_mul_f32_e32 v36, v40, v41
	v_pk_mul_f32 v[34:35], v[42:43], v[34:35]
	s_nop 0
	v_mul_f32_e32 v35, v34, v35
	v_cvt_pk_bf16_f32 v34, v58, v57
	v_cvt_pk_bf16_f32 v35, v36, v35
	global_store_dwordx2 v[54:55], v[34:35], off offset:-32
	s_nop 0
	v_mul_f32_e32 v43, v50, v56
	v_mov_b32_e32 v40, v148
	v_mov_b32_e32 v41, v149
	v_lshlrev_b32_e32 v42, 16, v40
	v_and_b32_e32 v58, 0xffff0000, v40
	v_lshlrev_b32_e32 v130, 16, v41
	v_and_b32_e32 v40, 0xffff0000, v41
	v_mul_f32_e32 v41, 0xbfb8aa3b, v42
	v_mov_b32_e32 v34, v160
	v_mov_b32_e32 v35, v161
	v_mov_b32_e32 v36, v162
	v_mov_b32_e32 v37, v163
	v_mov_b32_e32 v133, v34
	v_mul_f32_e32 v34, 0xbfb8aa3b, v58
	v_exp_f32_e32 v41, v41
	v_exp_f32_e32 v34, v34
	v_add_f32_e32 v41, 1.0, v41
	v_add_f32_e32 v34, 1.0, v34
	v_rcp_f32_e32 v132, v41
	v_rcp_f32_e32 v34, v34
	v_mul_f32_e32 v41, v49, v56
	v_mul_f32_e32 v49, v44, v56
	v_pk_mul_f32 v[42:43], v[132:133], v[42:43]
	v_pk_mul_f32 v[34:35], v[34:35], v[58:59]
	v_mul_f32_e32 v42, v42, v43
	v_mul_f32_e32 v43, v34, v35
	v_mul_f32_e32 v34, 0xbfb8aa3b, v130
	v_exp_f32_e32 v34, v34
	v_mov_b32_e32 v35, v36
	v_add_f32_e32 v34, 1.0, v34
	v_rcp_f32_e32 v34, v34
	s_nop 0
	v_pk_mul_f32 v[34:35], v[34:35], v[130:131]
	s_nop 0
	v_mul_f32_e32 v48, v34, v35
	v_mul_f32_e32 v34, 0xbfb8aa3b, v40
	v_exp_f32_e32 v34, v34
	s_nop 0
	v_add_f32_e32 v34, 1.0, v34
	v_rcp_f32_e32 v36, v34
	s_nop 0
	v_pk_mul_f32 v[34:35], v[36:37], v[40:41]
	s_nop 0
	v_mul_f32_e32 v35, v34, v35
	v_cvt_pk_bf16_f32 v34, v42, v43
	v_cvt_pk_bf16_f32 v35, v48, v35
	global_store_dwordx2 v[54:55], v[34:35], off
	s_nop 0
	v_mul_f32_e32 v43, v46, v56
	v_mov_b32_e32 v40, v150
	v_mov_b32_e32 v41, v151
	v_lshlrev_b32_e32 v42, 16, v40
	v_and_b32_e32 v40, 0xffff0000, v40
	v_mov_b32_e32 v34, v172
	v_mov_b32_e32 v35, v173
	v_mov_b32_e32 v36, v174
	v_mov_b32_e32 v37, v175
	v_mov_b32_e32 v53, v34
	v_mul_f32_e32 v34, 0xbfb8aa3b, v40
	v_exp_f32_e32 v34, v34
	v_lshlrev_b32_e32 v48, 16, v41
	v_and_b32_e32 v50, 0xffff0000, v41
	v_mul_f32_e32 v41, 0xbfb8aa3b, v42
	v_exp_f32_e32 v41, v41
	v_add_f32_e32 v34, 1.0, v34
	v_rcp_f32_e32 v34, v34
	v_add_f32_e32 v41, 1.0, v41
	v_rcp_f32_e32 v52, v41
	v_mul_f32_e32 v41, v47, v56
	v_pk_mul_f32 v[34:35], v[34:35], v[40:41]
	v_pk_mul_f32 v[42:43], v[52:53], v[42:43]
	v_mul_f32_e32 v40, v34, v35
	v_mul_f32_e32 v34, 0xbfb8aa3b, v48
	v_exp_f32_e32 v34, v34
	v_mov_b32_e32 v35, v36
	v_mul_f32_e32 v42, v42, v43
	v_add_f32_e32 v34, 1.0, v34
	v_rcp_f32_e32 v34, v34
	s_nop 0
	v_pk_mul_f32 v[34:35], v[34:35], v[48:49]
	s_nop 0
	v_mul_f32_e32 v41, v34, v35
	v_mul_f32_e32 v34, 0xbfb8aa3b, v50
	v_exp_f32_e32 v34, v34
	s_nop 0
	v_add_f32_e32 v34, 1.0, v34
	v_rcp_f32_e32 v36, v34
	s_nop 0
	v_pk_mul_f32 v[34:35], v[36:37], v[50:51]
	s_nop 0
	v_mul_f32_e32 v35, v34, v35
	v_cvt_pk_bf16_f32 v34, v42, v40
	v_cvt_pk_bf16_f32 v35, v41, v35
	global_store_dwordx2 v[54:55], v[34:35], off offset:32
	s_cbranch_scc1 .LBB0_176
	s_waitcnt lgkmcnt(0)
	v_readlane_b32 s98, v249, 49
	s_nop 0
	s_cmp_eq_u32 s98, 0x100
	s_cbranch_scc1 .Lsp3b_fast
	s_add_i32 s0, s0, s14
	s_cmpk_gt_i32 s0, 0xbff
	s_cbranch_scc0 .LBB0_175
	s_branch .LBB0_178

.LBB0_184:
	s_add_i32 s15, s15, 32
	s_mov_b64 s[22:23], 0x80000
	v_add_co_u32_e32 v6, vcc, 0xe8f84000, v0
	s_nop 0
	v_addc_co_u32_e32 v7, vcc, -1, v1, vcc
	global_load_dword v8, v[6:7], off nt
	v_add_co_u32_e32 v6, vcc, 0xe8f88000, v0
	s_nop 0
	v_addc_co_u32_e32 v7, vcc, -1, v1, vcc
	global_load_dword v9, v[6:7], off nt
	v_add_co_u32_e32 v6, vcc, 0xe8f8c000, v0
	s_nop 0
	v_addc_co_u32_e32 v7, vcc, -1, v1, vcc
	global_load_dword v10, v[6:7], off nt
	v_add_co_u32_e32 v6, vcc, 0xe8f90000, v0
	s_nop 0
	v_addc_co_u32_e32 v7, vcc, -1, v1, vcc
	global_load_dword v11, v[6:7], off nt
	v_add_co_u32_e32 v6, vcc, 0xe8f94000, v0
	s_nop 0
	v_addc_co_u32_e32 v7, vcc, -1, v1, vcc
	global_load_dword v12, v[6:7], off nt
	v_add_co_u32_e32 v6, vcc, 0xe8f98000, v0
	s_nop 0
	v_addc_co_u32_e32 v7, vcc, -1, v1, vcc
	global_load_dword v13, v[6:7], off nt
	v_add_co_u32_e32 v6, vcc, 0xe8f9c000, v0
	s_nop 0
	v_addc_co_u32_e32 v7, vcc, -1, v1, vcc
	global_load_dword v14, v[6:7], off nt
	v_add_co_u32_e32 v6, vcc, 0xe8fa0000, v0
	s_nop 0
	v_addc_co_u32_e32 v7, vcc, -1, v1, vcc
	global_load_dword v15, v[6:7], off nt
	v_add_co_u32_e32 v6, vcc, 0xe8fa4000, v0
	s_nop 0
	v_addc_co_u32_e32 v7, vcc, -1, v1, vcc
	global_load_dword v16, v[6:7], off nt
	v_add_co_u32_e32 v6, vcc, 0xe8fa8000, v0
	s_nop 0
	v_addc_co_u32_e32 v7, vcc, -1, v1, vcc
	global_load_dword v17, v[6:7], off nt
	v_add_co_u32_e32 v6, vcc, 0xe8fac000, v0
	s_nop 0
	v_addc_co_u32_e32 v7, vcc, -1, v1, vcc
	global_load_dword v18, v[6:7], off nt
	v_add_co_u32_e32 v6, vcc, 0xe8fb0000, v0
	s_nop 0
	v_addc_co_u32_e32 v7, vcc, -1, v1, vcc
	global_load_dword v19, v[6:7], off nt
	v_add_co_u32_e32 v6, vcc, 0xe8fb4000, v0
	s_nop 0
	v_addc_co_u32_e32 v7, vcc, -1, v1, vcc
	global_load_dword v20, v[6:7], off nt
	v_add_co_u32_e32 v6, vcc, 0xe8fb8000, v0
	s_nop 0
	v_addc_co_u32_e32 v7, vcc, -1, v1, vcc
	global_load_dword v21, v[6:7], off nt
	v_add_co_u32_e32 v6, vcc, 0xe8fbc000, v0
	s_nop 0
	v_addc_co_u32_e32 v7, vcc, -1, v1, vcc
	global_load_dword v22, v[6:7], off nt
	v_add_co_u32_e32 v6, vcc, 0xe8fc0000, v0
	s_nop 0
	v_addc_co_u32_e32 v7, vcc, -1, v1, vcc
	global_load_dword v23, v[6:7], off nt
	v_add_co_u32_e32 v6, vcc, 0xe8fc4000, v0
	s_nop 0
	v_addc_co_u32_e32 v7, vcc, -1, v1, vcc
	global_load_dword v24, v[6:7], off nt
	v_add_co_u32_e32 v6, vcc, 0xe8fc8000, v0
	s_nop 0
	v_addc_co_u32_e32 v7, vcc, -1, v1, vcc
	global_load_dword v25, v[6:7], off nt
	v_add_co_u32_e32 v6, vcc, 0xe8fcc000, v0
	s_nop 0
	v_addc_co_u32_e32 v7, vcc, -1, v1, vcc
	global_load_dword v26, v[6:7], off nt
	v_add_co_u32_e32 v6, vcc, 0xe8fd0000, v0
	s_nop 0
	v_addc_co_u32_e32 v7, vcc, -1, v1, vcc
	global_load_dword v27, v[6:7], off nt
	v_add_co_u32_e32 v6, vcc, 0xe8fd4000, v0
	s_nop 0
	v_addc_co_u32_e32 v7, vcc, -1, v1, vcc
	global_load_dword v28, v[6:7], off nt
	v_add_co_u32_e32 v6, vcc, 0xe8fd8000, v0
	s_nop 0
	v_addc_co_u32_e32 v7, vcc, -1, v1, vcc
	global_load_dword v29, v[6:7], off nt
	v_add_co_u32_e32 v6, vcc, 0xe8fdc000, v0
	s_nop 0
	v_addc_co_u32_e32 v7, vcc, -1, v1, vcc
	global_load_dword v30, v[6:7], off nt
	v_add_co_u32_e32 v6, vcc, 0xe8fe0000, v0
	s_nop 0
	v_addc_co_u32_e32 v7, vcc, -1, v1, vcc
	global_load_dword v31, v[6:7], off nt
	v_add_co_u32_e32 v6, vcc, 0xe8fe4000, v0
	s_nop 0
	v_addc_co_u32_e32 v7, vcc, -1, v1, vcc
	global_load_dword v32, v[6:7], off nt
	v_add_co_u32_e32 v6, vcc, 0xe8fe8000, v0
	s_nop 0
	v_addc_co_u32_e32 v7, vcc, -1, v1, vcc
	global_load_dword v34, v[6:7], off nt
	v_add_co_u32_e32 v6, vcc, 0xe8fec000, v0
	s_nop 0
	v_addc_co_u32_e32 v7, vcc, -1, v1, vcc
	global_load_dword v35, v[6:7], off nt
	v_add_co_u32_e32 v6, vcc, 0xe8ff0000, v0
	s_nop 0
	v_addc_co_u32_e32 v7, vcc, -1, v1, vcc
	global_load_dword v36, v[6:7], off nt
	v_add_co_u32_e32 v6, vcc, 0xe8ff4000, v0
	s_nop 0
	v_addc_co_u32_e32 v7, vcc, -1, v1, vcc
	global_load_dword v37, v[6:7], off nt
	v_add_co_u32_e32 v6, vcc, 0xe8ff8000, v0
	s_nop 0
	v_addc_co_u32_e32 v7, vcc, -1, v1, vcc
	global_load_dword v39, v[6:7], off nt
	v_add_co_u32_e32 v6, vcc, 0xe8ffc000, v0
	s_nop 0
	v_addc_co_u32_e32 v7, vcc, -1, v1, vcc
	global_load_dword v40, v[6:7], off nt
	v_add_co_u32_e32 v6, vcc, 0xe9000000, v0
	s_nop 0
	v_addc_co_u32_e32 v7, vcc, -1, v1, vcc
	global_load_dword v41, v[6:7], off nt
	s_waitcnt vmcnt(0)
	v_fmac_f32_e32 v8, v4, v5
	v_fmac_f32_e32 v9, v4, v8
	v_fmac_f32_e32 v10, v4, v9
	v_fmac_f32_e32 v11, v4, v10
	v_fmac_f32_e32 v12, v4, v11
	v_fmac_f32_e32 v13, v4, v12
	v_fmac_f32_e32 v14, v4, v13
	v_fmac_f32_e32 v15, v4, v14
	v_fmac_f32_e32 v16, v4, v15
	v_fmac_f32_e32 v17, v4, v16
	v_fmac_f32_e32 v18, v4, v17
	v_fmac_f32_e32 v19, v4, v18
	v_fmac_f32_e32 v20, v4, v19
	v_fmac_f32_e32 v21, v4, v20
	v_fmac_f32_e32 v22, v4, v21
	v_fmac_f32_e32 v23, v4, v22
	v_fmac_f32_e32 v24, v4, v23
	v_fmac_f32_e32 v25, v4, v24
	v_fmac_f32_e32 v26, v4, v25
	v_fmac_f32_e32 v27, v4, v26
	v_fmac_f32_e32 v28, v4, v27
	v_fmac_f32_e32 v29, v4, v28
	v_fmac_f32_e32 v30, v4, v29
	v_fmac_f32_e32 v31, v4, v30
	v_fmac_f32_e32 v32, v4, v31
	v_fmac_f32_e32 v34, v4, v32
	v_fmac_f32_e32 v35, v4, v34
	v_fmac_f32_e32 v36, v4, v35
	v_fmac_f32_e32 v37, v4, v36
	v_fmac_f32_e32 v39, v4, v37
	v_fmac_f32_e32 v40, v4, v39
	v_fmac_f32_e32 v41, v4, v40
	v_add_co_u32_e32 v6, vcc, 0xfff84000, v0
	s_nop 0
	v_addc_co_u32_e32 v7, vcc, -1, v1, vcc
	s_nop 0
	global_store_dword v[6:7], v5, off
	v_add_co_u32_e32 v6, vcc, 0xfff88000, v0
	s_nop 0
	v_addc_co_u32_e32 v7, vcc, -1, v1, vcc
	s_nop 0
	global_store_dword v[6:7], v8, off
	v_add_co_u32_e32 v6, vcc, 0xfff8c000, v0
	s_nop 0
	v_addc_co_u32_e32 v7, vcc, -1, v1, vcc
	s_nop 0
	global_store_dword v[6:7], v9, off
	global_store_dword v[0:1], v40, off
	v_add_co_u32_e32 v6, vcc, 0xfff90000, v0
	s_nop 0
	v_addc_co_u32_e32 v7, vcc, -1, v1, vcc
	s_nop 0
	global_store_dword v[6:7], v10, off
	v_add_co_u32_e32 v6, vcc, 0xfff94000, v0
	s_nop 0
	v_addc_co_u32_e32 v7, vcc, -1, v1, vcc
	s_nop 0
	global_store_dword v[6:7], v11, off
	v_add_co_u32_e32 v6, vcc, 0xfff98000, v0
	s_nop 0
	v_addc_co_u32_e32 v7, vcc, -1, v1, vcc
	s_nop 0
	global_store_dword v[6:7], v12, off
	v_add_co_u32_e32 v6, vcc, 0xfff9c000, v0
	s_nop 0
	v_addc_co_u32_e32 v7, vcc, -1, v1, vcc
	s_nop 0
	global_store_dword v[6:7], v13, off
	v_add_co_u32_e32 v6, vcc, 0xfffa0000, v0
	s_nop 0
	v_addc_co_u32_e32 v7, vcc, -1, v1, vcc
	s_nop 0
	global_store_dword v[6:7], v14, off
	v_add_co_u32_e32 v6, vcc, 0xfffa4000, v0
	s_nop 0
	v_addc_co_u32_e32 v7, vcc, -1, v1, vcc
	s_nop 0
	global_store_dword v[6:7], v15, off
	v_add_co_u32_e32 v6, vcc, 0xfffa8000, v0
	s_nop 0
	v_addc_co_u32_e32 v7, vcc, -1, v1, vcc
	s_nop 0
	global_store_dword v[6:7], v16, off
	v_add_co_u32_e32 v6, vcc, 0xfffac000, v0
	s_nop 0
	v_addc_co_u32_e32 v7, vcc, -1, v1, vcc
	s_nop 0
	global_store_dword v[6:7], v17, off
	v_add_co_u32_e32 v6, vcc, 0xfffb0000, v0
	s_nop 0
	v_addc_co_u32_e32 v7, vcc, -1, v1, vcc
	s_nop 0
	global_store_dword v[6:7], v18, off
	v_add_co_u32_e32 v6, vcc, 0xfffb4000, v0
	s_nop 0
	v_addc_co_u32_e32 v7, vcc, -1, v1, vcc
	s_nop 0
	global_store_dword v[6:7], v19, off
	v_add_co_u32_e32 v6, vcc, 0xfffb8000, v0
	s_nop 0
	v_addc_co_u32_e32 v7, vcc, -1, v1, vcc
	s_nop 0
	global_store_dword v[6:7], v20, off
	v_add_co_u32_e32 v6, vcc, 0xfffbc000, v0
	s_nop 0
	v_addc_co_u32_e32 v7, vcc, -1, v1, vcc
	s_nop 0
	global_store_dword v[6:7], v21, off
	v_add_co_u32_e32 v6, vcc, 0xfffc0000, v0
	s_nop 0
	v_addc_co_u32_e32 v7, vcc, -1, v1, vcc
	s_nop 0
	global_store_dword v[6:7], v22, off
	v_add_co_u32_e32 v6, vcc, 0xfffc4000, v0
	s_nop 0
	v_addc_co_u32_e32 v7, vcc, -1, v1, vcc
	s_nop 0
	global_store_dword v[6:7], v23, off
	v_add_co_u32_e32 v6, vcc, 0xfffc8000, v0
	s_nop 0
	v_addc_co_u32_e32 v7, vcc, -1, v1, vcc
	s_nop 0
	global_store_dword v[6:7], v24, off
	v_add_co_u32_e32 v6, vcc, 0xfffcc000, v0
	s_nop 0
	v_addc_co_u32_e32 v7, vcc, -1, v1, vcc
	s_nop 0
	global_store_dword v[6:7], v25, off
	v_add_co_u32_e32 v6, vcc, 0xfffd0000, v0
	s_nop 0
	v_addc_co_u32_e32 v7, vcc, -1, v1, vcc
	s_nop 0
	global_store_dword v[6:7], v26, off
	v_add_co_u32_e32 v6, vcc, 0xfffd4000, v0
	s_nop 0
	v_addc_co_u32_e32 v7, vcc, -1, v1, vcc
	s_nop 0
	global_store_dword v[6:7], v27, off
	v_add_co_u32_e32 v6, vcc, 0xfffd8000, v0
	s_nop 0
	v_addc_co_u32_e32 v7, vcc, -1, v1, vcc
	s_nop 0
	global_store_dword v[6:7], v28, off
	v_add_co_u32_e32 v6, vcc, 0xfffdc000, v0
	s_nop 0
	v_addc_co_u32_e32 v7, vcc, -1, v1, vcc
	s_nop 0
	global_store_dword v[6:7], v29, off
	v_add_co_u32_e32 v6, vcc, 0xfffe0000, v0
	s_nop 0
	v_addc_co_u32_e32 v7, vcc, -1, v1, vcc
	s_nop 0
	global_store_dword v[6:7], v30, off
	v_add_co_u32_e32 v6, vcc, 0xfffe4000, v0
	s_nop 0
	v_addc_co_u32_e32 v7, vcc, -1, v1, vcc
	s_nop 0
	global_store_dword v[6:7], v31, off
	v_add_co_u32_e32 v6, vcc, 0xfffe8000, v0
	s_nop 0
	v_addc_co_u32_e32 v7, vcc, -1, v1, vcc
	s_nop 0
	global_store_dword v[6:7], v32, off
	v_add_co_u32_e32 v6, vcc, 0xfffec000, v0
	s_nop 0
	v_addc_co_u32_e32 v7, vcc, -1, v1, vcc
	s_nop 0
	global_store_dword v[6:7], v34, off
	v_add_co_u32_e32 v6, vcc, 0xffff0000, v0
	s_nop 0
	v_addc_co_u32_e32 v7, vcc, -1, v1, vcc
	s_nop 0
	global_store_dword v[6:7], v35, off
	v_add_co_u32_e32 v6, vcc, 0xffff4000, v0
	s_nop 0
	v_addc_co_u32_e32 v7, vcc, -1, v1, vcc
	s_nop 0
	global_store_dword v[6:7], v36, off
	v_add_co_u32_e32 v6, vcc, 0xffff8000, v0
	s_nop 0
	v_addc_co_u32_e32 v7, vcc, -1, v1, vcc
	s_nop 0
	global_store_dword v[6:7], v37, off
	v_add_co_u32_e32 v6, vcc, 0xffffc000, v0
	s_nop 0
	v_addc_co_u32_e32 v7, vcc, -1, v1, vcc
	s_nop 0
	global_store_dword v[6:7], v39, off
	v_mov_b32_e32 v5, v41
	v_lshl_add_u64 v[0:1], v[0:1], 0, s[22:23]
	s_cmpk_gt_u32 s15, 0xdf
	s_cbranch_scc0 .LBB0_184
	v_add_u32_e32 v2, s12, v2
	s_mov_b32 s15, 0xbfff
	v_cmp_lt_i32_e32 vcc, s15, v2
	s_or_b64 s[20:21], vcc, s[20:21]
	v_add_u16_e32 v3, s12, v3
	s_andn2_b64 exec, exec, s[20:21]
	s_cbranch_execnz .LBB0_183
